# full C tile loop control cleanup: barrier selection, post-barrier flag glue, vote-word read order, tile DMA from MFMA gaps, rare blocks out of line
# speedup vs baseline: 1.0077x; 1.0046x over previous
; #define SBAR() __builtin_amdgcn_sched_barrier(0)
; #define PIN(x) asm volatile("" : "+v"(x))
; #define MF(a_, b_, c_) __builtin_amdgcn_mfma_f32_32x32x16_bf16(a_, b_, c_, 0, 0, 0)
; #define LDV(j_) do { if ((j_) < 4 * NDB) { const lds_cptr a_ = vp + ((j_) % NDB) * 4096 + ((j_) / NDB) * 1024; const s16x4 lo_ = vtr(a_), hi_ = vtr(a_ + 512); \
;             vq[(j_) & 3] = (bf16x8){lo_[0], lo_[1], lo_[2], lo_[3], hi_[0], hi_[1], hi_[2], hi_[3]}; } } while (0)
; #define PVM(j_) o[(j_) % NDB] = MF(vq[(j_) & 3], pw[(j_) / NDB], o[(j_) % NDB])
; #define E4(a_, W_, j_) do { pa1[a_] = EX(pa1[a_]); pa1[a_ + 1] = EX(pa1[a_ + 1]); sacc += pa1[a_]; sacc += pa1[a_ + 1]; W_[j_] = cvtpk(pa1[a_], pa1[a_ + 1]); } while (0)
; template <int KIND> DI void attn_unit(const Params& P, int b, int h, int qb, char* shm, float lam, bool dry = false) {
;     ...
;         if (KIND == 2) { pb0 = MF(x0, ones, pb0); pb1 = MF(x1, ones, pb1); }
;         pw[0] = __builtin_bit_cast(bf16x8, w0); pw[1] = __builtin_bit_cast(bf16x8, w1);
;     ...
;         if (NDB == 4) {
;             LDV(3); PVM(0); E4(0, w0, 0); PIN(pa1); PIN(sacc); PIN(w0); SBAR();
;             LDV(4); PVM(1); E4(2, w0, 1); PIN(pa1); PIN(sacc); PIN(w0); SBAR();
;             LDV(5); PVM(2); E4(4, w0, 2); PIN(pa1); PIN(sacc); PIN(w0); SBAR();
;             LDV(6); PVM(3); E4(6, w0, 3); PIN(pa1); PIN(sacc); PIN(w0); SBAR();
;             LDV(7); PVM(4); E4(8, w1, 0); PIN(pa1); PIN(sacc); PIN(w1); SBAR();
;             LDV(8); PVM(5); E4(10, w1, 1); PIN(pa1); PIN(sacc); PIN(w1); SBAR();
;             LDV(9); PVM(6); E4(12, w1, 2); PIN(pa1); PIN(sacc); PIN(w1); SBAR();
;             LDV(10); PVM(7); E4(14, w1, 3); PIN(pa1); PIN(sacc); PIN(w1); SBAR();
;         } else {
;             LDV(3); PVM(0); E4(0, w0, 0); E4(2, w0, 1); PIN(pa1); PIN(sacc); PIN(w0); SBAR();
;             LDV(4); PVM(1); E4(4, w0, 2); E4(6, w0, 3); PIN(pa1); PIN(sacc); PIN(w0); SBAR();
;             LDV(5); PVM(2); E4(8, w1, 0); E4(10, w1, 1); PIN(pa1); PIN(sacc); PIN(w1); SBAR();
;             LDV(6); PVM(3); E4(12, w1, 2); E4(14, w1, 3); PIN(pa1); PIN(sacc); PIN(w1); SBAR();
;         }
;     ...
;         pw[2] = __builtin_bit_cast(bf16x8, w0); pw[3] = __builtin_bit_cast(bf16x8, w1);
;         lsum += sacc;
;         ATT_FIX(pb0, pb1, ATT_TILE(i + 1));
.Lct1_nd2:
	v_exp_f32_e32 v10, v10
	v_exp_f32_e32 v11, v11
	v_add_f32_e32 v74, v76, v8
	ds_read_b64_tr_b16 v[116:117], v164 offset:18432
	ds_read_b64_tr_b16 v[118:119], v164 offset:18944
	v_add_f32_e32 v75, v9, v74
	v_add_f32_e32 v75, v10, v75
	v_cvt_pk_bf16_f32 v192, v8, v9
	v_add_f32_e32 v76, v11, v75
	v_cvt_pk_bf16_f32 v193, v10, v11
	v_exp_f32_e32 v12, v12
	s_waitcnt lgkmcnt(4)
	v_mfma_f32_32x32x16_bf16 v[52:67], v[124:127], v[148:151], v[52:67]
	v_exp_f32_e32 v13, v13
	v_exp_f32_e32 v14, v14
	ds_read_b64_tr_b16 v[120:121], v164 offset:22528
	ds_read_b64_tr_b16 v[122:123], v164 offset:23040
	v_exp_f32_e32 v15, v15
	v_add_f32_e32 v72, v76, v12
	v_add_f32_e32 v76, v13, v72
	v_cvt_pk_bf16_f32 v152, v12, v13
	v_add_f32_e32 v73, v14, v76
	v_add_f32_e32 v76, v15, v73
	v_cvt_pk_bf16_f32 v153, v14, v15
	s_waitcnt lgkmcnt(4)
	v_mfma_f32_32x32x16_bf16 v[36:51], v[68:71], v[148:151], v[36:51]
	v_exp_f32_e32 v16, v16
	v_exp_f32_e32 v17, v17
	v_exp_f32_e32 v18, v18
	v_exp_f32_e32 v19, v19
	ds_read_b64_tr_b16 v[124:125], v164 offset:19456
	ds_read_b64_tr_b16 v[126:127], v164 offset:19968
	v_add_f32_e32 v68, v76, v16
	v_add_f32_e32 v68, v17, v68
	v_cvt_pk_bf16_f32 v154, v16, v17
	v_cvt_pk_bf16_f32 v155, v18, v19
	v_add_f32_e32 v68, v18, v68
	v_add_f32_e32 v68, v19, v68
	s_cmp_lg_u32 s22, s35
	s_cbranch_scc0 .Lhotc1_diag

; #define SBAR() __builtin_amdgcn_sched_barrier(0)
; #define PIN(x) asm volatile("" : "+v"(x))
; #define MF(a_, b_, c_) __builtin_amdgcn_mfma_f32_32x32x16_bf16(a_, b_, c_, 0, 0, 0)
; #define LDV(j_) do { if ((j_) < 4 * NDB) { const lds_cptr a_ = vp + ((j_) % NDB) * 4096 + ((j_) / NDB) * 1024; const s16x4 lo_ = vtr(a_), hi_ = vtr(a_ + 512); \
;             vq[(j_) & 3] = (bf16x8){lo_[0], lo_[1], lo_[2], lo_[3], hi_[0], hi_[1], hi_[2], hi_[3]}; } } while (0)
; #define PVM(j_) o[(j_) % NDB] = MF(vq[(j_) & 3], pw[(j_) / NDB], o[(j_) % NDB])
; #define E4(a_, W_, j_) do { pa1[a_] = EX(pa1[a_]); pa1[a_ + 1] = EX(pa1[a_ + 1]); sacc += pa1[a_]; sacc += pa1[a_ + 1]; W_[j_] = cvtpk(pa1[a_], pa1[a_ + 1]); } while (0)
; template <int KIND> DI void attn_unit(const Params& P, int b, int h, int qb, char* shm, float lam, bool dry = false) {
;     ...
;         if (KIND == 2) { pb0 = MF(x0, ones, pb0); pb1 = MF(x1, ones, pb1); }
;         pw[0] = __builtin_bit_cast(bf16x8, w0); pw[1] = __builtin_bit_cast(bf16x8, w1);
;     ...
;         if (NDB == 4) {
;             LDV(3); PVM(0); E4(0, w0, 0); PIN(pa1); PIN(sacc); PIN(w0); SBAR();
;             LDV(4); PVM(1); E4(2, w0, 1); PIN(pa1); PIN(sacc); PIN(w0); SBAR();
;             LDV(5); PVM(2); E4(4, w0, 2); PIN(pa1); PIN(sacc); PIN(w0); SBAR();
;             LDV(6); PVM(3); E4(6, w0, 3); PIN(pa1); PIN(sacc); PIN(w0); SBAR();
;             LDV(7); PVM(4); E4(8, w1, 0); PIN(pa1); PIN(sacc); PIN(w1); SBAR();
;             LDV(8); PVM(5); E4(10, w1, 1); PIN(pa1); PIN(sacc); PIN(w1); SBAR();
;             LDV(9); PVM(6); E4(12, w1, 2); PIN(pa1); PIN(sacc); PIN(w1); SBAR();
;             LDV(10); PVM(7); E4(14, w1, 3); PIN(pa1); PIN(sacc); PIN(w1); SBAR();
;         } else {
;             LDV(3); PVM(0); E4(0, w0, 0); E4(2, w0, 1); PIN(pa1); PIN(sacc); PIN(w0); SBAR();
;             LDV(4); PVM(1); E4(4, w0, 2); E4(6, w0, 3); PIN(pa1); PIN(sacc); PIN(w0); SBAR();
;             LDV(5); PVM(2); E4(8, w1, 0); E4(10, w1, 1); PIN(pa1); PIN(sacc); PIN(w1); SBAR();
;             LDV(6); PVM(3); E4(12, w1, 2); E4(14, w1, 3); PIN(pa1); PIN(sacc); PIN(w1); SBAR();
;         }
;     ...
;         pw[2] = __builtin_bit_cast(bf16x8, w0); pw[3] = __builtin_bit_cast(bf16x8, w1);
;         lsum += sacc;
;         ATT_FIX(pb0, pb1, ATT_TILE(i + 1));
.Lct2x_nd2:
	v_exp_f32_e32 v106, v106
	v_exp_f32_e32 v107, v107
	v_add_f32_e32 v74, v76, v104
	ds_read_b64_tr_b16 v[84:85], v164 offset:18432
	ds_read_b64_tr_b16 v[86:87], v164 offset:18944
	v_add_f32_e32 v75, v105, v74
	v_add_f32_e32 v75, v106, v75
	v_cvt_pk_bf16_f32 v192, v104, v105
	v_add_f32_e32 v76, v107, v75
	v_cvt_pk_bf16_f32 v193, v106, v107
	v_exp_f32_e32 v108, v108
	s_waitcnt lgkmcnt(4)
	v_mfma_f32_32x32x16_bf16 v[52:67], v[92:95], v[148:151], v[52:67]
	v_exp_f32_e32 v109, v109
	v_exp_f32_e32 v110, v110
	ds_read_b64_tr_b16 v[88:89], v164 offset:22528
	ds_read_b64_tr_b16 v[90:91], v164 offset:23040
	v_exp_f32_e32 v111, v111
	v_add_f32_e32 v72, v76, v108
	v_add_f32_e32 v76, v109, v72
	v_cvt_pk_bf16_f32 v152, v108, v109
	v_add_f32_e32 v73, v110, v76
	v_add_f32_e32 v76, v111, v73
	v_cvt_pk_bf16_f32 v153, v110, v111
	s_waitcnt lgkmcnt(4)
	v_mfma_f32_32x32x16_bf16 v[36:51], v[68:71], v[148:151], v[36:51]
	v_exp_f32_e32 v112, v112
	v_exp_f32_e32 v113, v113
	v_exp_f32_e32 v114, v114
	v_exp_f32_e32 v115, v115
	ds_read_b64_tr_b16 v[92:93], v164 offset:19456
	ds_read_b64_tr_b16 v[94:95], v164 offset:19968
	v_add_f32_e32 v68, v76, v112
	v_add_f32_e32 v68, v113, v68
	v_cvt_pk_bf16_f32 v154, v112, v113
	v_cvt_pk_bf16_f32 v155, v114, v115
	v_add_f32_e32 v68, v114, v68
	v_add_f32_e32 v68, v115, v68
	s_cmp_lg_u32 s22, s35
	s_cbranch_scc0 .Lhotc2_diag
